# v13: + CMP2 with 4 K-chunks of loads in flight; table fill once per unit pair
# speedup vs baseline: 1.0003x; 1.0003x over previous
.LBB0_449:
	v_lshl_add_u64 v[22:23], v[8:9], 0, s[12:13]
	v_lshl_add_u64 v[22:23], v[22:23], 0, s[8:9]
	v_lshl_add_u64 v[34:35], v[6:7], 0, s[10:11]
	v_lshl_add_u64 v[34:35], v[34:35], 0, s[10:11]
	global_load_dword v72, v[6:7], off offset:-1792
	global_load_dword v73, v[6:7], off offset:-1536
	global_load_dword v74, v[6:7], off offset:-1280
	global_load_dword v75, v[6:7], off offset:-1024
	global_load_dword v76, v[6:7], off offset:-768
	global_load_dword v77, v[6:7], off offset:-512
	global_load_dword v78, v[6:7], off offset:-256
	global_load_dword v79, v[6:7], off offset:0
	global_load_dwordx4 v[40:43], v[22:23], off offset:0
	global_load_dwordx4 v[44:47], v[22:23], off offset:16
	global_load_dword v80, v[6:7], off offset:256
	global_load_dword v81, v[6:7], off offset:512
	global_load_dword v82, v[6:7], off offset:768
	global_load_dword v83, v[6:7], off offset:1024
	global_load_dword v84, v[6:7], off offset:1280
	global_load_dword v85, v[6:7], off offset:1536
	global_load_dword v86, v[6:7], off offset:1792
	global_load_dword v87, v[6:7], off offset:2048
	global_load_dwordx4 v[48:51], v[22:23], off offset:32
	global_load_dwordx4 v[52:55], v[22:23], off offset:48
	global_load_dword v88, v[34:35], off offset:-1792
	global_load_dword v89, v[34:35], off offset:-1536
	global_load_dword v90, v[34:35], off offset:-1280
	global_load_dword v91, v[34:35], off offset:-1024
	global_load_dword v92, v[34:35], off offset:-768
	global_load_dword v93, v[34:35], off offset:-512
	global_load_dword v94, v[34:35], off offset:-256
	global_load_dword v95, v[34:35], off offset:0
	global_load_dwordx4 v[56:59], v[22:23], off offset:64
	global_load_dwordx4 v[60:63], v[22:23], off offset:80
	global_load_dword v96, v[34:35], off offset:256
	global_load_dword v97, v[34:35], off offset:512
	global_load_dword v98, v[34:35], off offset:768
	global_load_dword v99, v[34:35], off offset:1024
	global_load_dword v100, v[34:35], off offset:1280
	global_load_dword v101, v[34:35], off offset:1536
	global_load_dword v102, v[34:35], off offset:1792
	global_load_dword v103, v[34:35], off offset:2048
	global_load_dwordx4 v[64:67], v[22:23], off offset:96
	global_load_dwordx4 v[68:71], v[22:23], off offset:112
	s_add_u32 s12, s12, 0x80
	s_addc_u32 s13, s13, 0
	v_add_co_u32_e32 v6, vcc, 0x2000, v6
	s_nop 1
	v_addc_co_u32_e32 v7, vcc, 0, v7, vcc
	s_cmpk_eq_i32 s12, 0x400
	s_waitcnt vmcnt(0)
	v_fmac_f32_e32 v17, v40, v72
	v_fmac_f32_e32 v17, v41, v73
	v_fmac_f32_e32 v17, v42, v74
	v_fmac_f32_e32 v17, v43, v75
	v_fmac_f32_e32 v17, v44, v76
	v_fmac_f32_e32 v17, v45, v77
	v_fmac_f32_e32 v17, v46, v78
	v_fmac_f32_e32 v17, v47, v79
	v_fmac_f32_e32 v17, v48, v80
	v_fmac_f32_e32 v17, v49, v81
	v_fmac_f32_e32 v17, v50, v82
	v_fmac_f32_e32 v17, v51, v83
	v_fmac_f32_e32 v17, v52, v84
	v_fmac_f32_e32 v17, v53, v85
	v_fmac_f32_e32 v17, v54, v86
	v_fmac_f32_e32 v17, v55, v87
	v_fmac_f32_e32 v17, v56, v88
	v_fmac_f32_e32 v17, v57, v89
	v_fmac_f32_e32 v17, v58, v90
	v_fmac_f32_e32 v17, v59, v91
	v_fmac_f32_e32 v17, v60, v92
	v_fmac_f32_e32 v17, v61, v93
	v_fmac_f32_e32 v17, v62, v94
	v_fmac_f32_e32 v17, v63, v95
	v_fmac_f32_e32 v17, v64, v96
	v_fmac_f32_e32 v17, v65, v97
	v_fmac_f32_e32 v17, v66, v98
	v_fmac_f32_e32 v17, v67, v99
	v_fmac_f32_e32 v17, v68, v100
	v_fmac_f32_e32 v17, v69, v101
	v_fmac_f32_e32 v17, v70, v102
	v_fmac_f32_e32 v17, v71, v103
	s_cbranch_scc0 .LBB0_449
	v_and_b32_e32 v8, 0xfff, v0
	v_and_b32_e32 v0, 0x1fc0, v10
	v_cmp_ne_u32_e32 vcc, s15, v0
	v_add_u32_e32 v10, s0, v10
	s_nop 0
	v_cndmask_b32_e32 v0, 0, v17, vcc
	v_bfe_u32 v6, v0, 16, 1
	v_add3_u32 v9, v0, v6, s17
	v_cndmask_b32_e64 v0, v15, v16, s[2:3]
	v_lshl_add_u64 v[6:7], s[26:27], 0, v[0:1]
	v_lshlrev_b32_e32 v0, 7, v8
	v_lshl_add_u64 v[6:7], v[6:7], 0, v[0:1]
	v_cmp_lt_i32_e32 vcc, s18, v10
	v_lshl_add_u64 v[6:7], v[6:7], 0, v[4:5]
	s_or_b64 s[6:7], vcc, s[6:7]
	global_store_short_d16_hi v[6:7], v9, off
	s_andn2_b64 exec, exec, s[6:7]
	s_cbranch_execnz .LBB0_448
